# speculative first-half exp under PV(B) MFMA shadow (recomputed on rescale path) + K addr calc before barriers + K prefetch first after step-B barrier
# baseline (speedup 1.0000x reference)
.LBB0_307:
	v_lshlrev_b32_e32 v4, 1, v196
	s_lshr_b32 s44, s75, 6
	v_lshlrev_b32_e32 v3, 4, v196
	v_and_b32_e32 v4, 32, v4
	s_movk_i32 s2, 0xc0
	v_and_or_b32 v3, v3, s2, v4
	v_and_b32_e32 v1, 0x100, v1
	s_cmp_lg_u32 0, -1
	v_or3_b32 v1, v3, v1, v2
	s_cselect_b32 s2, 0, 0
	v_add_u32_e32 v206, s2, v1
	v_max_f32_e32 v1, v35, v35
	v_max_f32_e32 v2, v34, v34
	v_max_f32_e32 v1, v2, v1
	v_max3_f32 v1, v1, v36, v37
	v_max3_f32 v1, v1, v38, v39
	v_max3_f32 v1, v1, v40, v41
	v_max3_f32 v1, v1, v42, v43
	v_max3_f32 v1, v1, v44, v45
	v_max3_f32 v1, v1, v46, v47
	v_max3_f32 v1, v1, v48, v49
	v_max3_f32 v1, v1, v18, v19
	v_max3_f32 v1, v1, v20, v21
	v_max3_f32 v1, v1, v22, v23
	v_max3_f32 v1, v1, v24, v25
	v_max3_f32 v1, v1, v26, v27
	v_max3_f32 v1, v1, v28, v29
	v_max3_f32 v1, v1, v30, v31
	v_max3_f32 v1, v1, v32, v33
	v_mov_b32_e32 v2, v1
	s_nop 1
	v_permlane32_swap_b32_e32 v1, v2
	v_max_f32_e32 v2, v2, v2
	v_max_f32_e32 v1, v1, v1
	v_max_f32_e32 v1, v1, v2
	v_add_f32_e32 v2, 0x7149f2ca, v1
	v_mul_f32_e32 v2, 0x3db504f3, v2
	v_max_f32_e32 v1, 0xf149f2ca, v1
	v_cmp_ge_f32_e32 vcc, s84, v2
	v_sub_f32_e32 v2, 0xf149f2ca, v1
	v_mul_f32_e32 v2, 0x3e0293ee, v2
	v_exp_f32_e32 v2, v2
	s_cmp_eq_u64 vcc, exec
	s_cselect_b64 vcc, -1, 0
	v_cndmask_b32_e32 v214, v1, v194, vcc
	v_cndmask_b32_e64 v213, v2, 1.0, vcc
	v_mul_f32_e32 v2, 0xbe0293ee, v214
	v_fmamk_f32 v3, v35, 0x3e0293ee, v2
	v_mov_b32_e32 v35, v2
	v_fmamk_f32 v1, v34, 0x3e0293ee, v2
	v_fmamk_f32 v4, v36, 0x3e0293ee, v2
	v_fmamk_f32 v5, v37, 0x3e0293ee, v2
	v_fmamk_f32 v6, v38, 0x3e0293ee, v2
	v_fmamk_f32 v7, v39, 0x3e0293ee, v2
	v_fmamk_f32 v8, v40, 0x3e0293ee, v2
	v_fmamk_f32 v9, v41, 0x3e0293ee, v2
	v_fmamk_f32 v10, v42, 0x3e0293ee, v2
	v_fmamk_f32 v11, v43, 0x3e0293ee, v2
	v_fmamk_f32 v12, v44, 0x3e0293ee, v2
	v_fmamk_f32 v13, v45, 0x3e0293ee, v2
	v_fmamk_f32 v14, v46, 0x3e0293ee, v2
	v_fmamk_f32 v15, v47, 0x3e0293ee, v2
	v_fmamk_f32 v34, v48, 0x3e0293ee, v2
	v_fmac_f32_e32 v35, 0x3e0293ee, v49
	v_exp_f32_e32 v230, v1
	v_exp_f32_e32 v232, v3
	v_exp_f32_e32 v228, v4
	v_exp_f32_e32 v231, v5
	v_exp_f32_e32 v226, v6
	v_exp_f32_e32 v229, v7
	v_exp_f32_e32 v225, v8
	v_exp_f32_e32 v227, v9
	v_exp_f32_e32 v222, v10
	v_exp_f32_e32 v224, v11
	v_exp_f32_e32 v220, v12
	v_exp_f32_e32 v223, v13
	v_exp_f32_e32 v218, v14
	v_exp_f32_e32 v221, v15
	v_exp_f32_e32 v217, v34
	v_exp_f32_e32 v219, v35
	s_waitcnt vmcnt(4) lgkmcnt(0)
	s_barrier
	s_mov_b32 s56, 1
	v_pk_fma_f32 v[142:143], v[32:33], s[12:13], v[2:3] op_sel_hi:[1,0,0]
	v_pk_fma_f32 v[140:141], v[30:31], s[12:13], v[2:3] op_sel_hi:[1,0,0]
	v_pk_fma_f32 v[138:139], v[28:29], s[12:13], v[2:3] op_sel_hi:[1,0,0]
	v_pk_fma_f32 v[136:137], v[26:27], s[12:13], v[2:3] op_sel_hi:[1,0,0]
	v_pk_fma_f32 v[134:135], v[24:25], s[12:13], v[2:3] op_sel_hi:[1,0,0]
	v_pk_fma_f32 v[132:133], v[22:23], s[12:13], v[2:3] op_sel_hi:[1,0,0]
	v_pk_fma_f32 v[130:131], v[20:21], s[12:13], v[2:3] op_sel_hi:[1,0,0]
	v_pk_fma_f32 v[128:129], v[18:19], s[12:13], v[2:3] op_sel_hi:[1,0,0]
	s_cmpk_lt_u32 s75, 0x1c0
	v_cmp_gt_u32_e64 s[2:3], 32, v196
	v_lshl_add_u32 v204, v201, 2, s92
	v_lshl_add_u32 v203, v202, 2, s92
	s_cbranch_scc1 .LBB0_319
	s_add_i32 s21, s44, -4
	s_add_u32 s56, s58, 0x8000
	s_addc_u32 s57, s59, 0
	v_mov_b32_e32 v14, v0
	v_mov_b32_e32 v15, v0
	s_add_u32 s70, s4, 0x10000
	v_mov_b32_e32 v1, v0
	v_mov_b32_e32 v2, v0
	v_mov_b32_e32 v3, v0
	v_mov_b32_e32 v4, v0
	v_mov_b32_e32 v5, v0
	v_mov_b32_e32 v6, v0
	v_mov_b32_e32 v7, v0
	v_mov_b32_e32 v8, v0
	v_mov_b32_e32 v9, v0
	v_mov_b32_e32 v10, v0
	v_mov_b32_e32 v11, v0
	v_mov_b32_e32 v12, v0
	v_mov_b32_e32 v13, v0
	v_mov_b64_e32 v[46:47], v[14:15]
	v_mov_b64_e32 v[62:63], v[14:15]
	v_mov_b64_e32 v[78:79], v[14:15]
	v_mov_b64_e32 v[94:95], v[14:15]
	s_mov_b32 s45, 2
	s_addc_u32 s71, s5, 0
	v_mov_b32_e32 v205, 0
	v_mov_b64_e32 v[44:45], v[12:13]
	v_mov_b64_e32 v[42:43], v[10:11]
	v_mov_b64_e32 v[40:41], v[8:9]
	v_mov_b64_e32 v[38:39], v[6:7]
	v_mov_b64_e32 v[36:37], v[4:5]
	v_mov_b64_e32 v[34:35], v[2:3]
	v_mov_b64_e32 v[32:33], v[0:1]
	v_mov_b64_e32 v[60:61], v[12:13]
	v_mov_b64_e32 v[58:59], v[10:11]
	v_mov_b64_e32 v[56:57], v[8:9]
	v_mov_b64_e32 v[54:55], v[6:7]
	v_mov_b64_e32 v[52:53], v[4:5]
	v_mov_b64_e32 v[50:51], v[2:3]
	v_mov_b64_e32 v[48:49], v[0:1]
	v_mov_b64_e32 v[76:77], v[12:13]
	v_mov_b64_e32 v[74:75], v[10:11]
	v_mov_b64_e32 v[72:73], v[8:9]
	v_mov_b64_e32 v[70:71], v[6:7]
	v_mov_b64_e32 v[68:69], v[4:5]
	v_mov_b64_e32 v[66:67], v[2:3]
	v_mov_b64_e32 v[64:65], v[0:1]
	v_mov_b64_e32 v[92:93], v[12:13]
	v_mov_b64_e32 v[90:91], v[10:11]
	v_mov_b64_e32 v[88:89], v[8:9]
	v_mov_b64_e32 v[86:87], v[6:7]
	v_mov_b64_e32 v[84:85], v[4:5]
	v_mov_b64_e32 v[82:83], v[2:3]
	v_mov_b64_e32 v[80:81], v[0:1]
	v_add3_u32 v215, s74, v209, v208
	v_add3_u32 v216, s74, v210, v208
	v_add3_u32 v233, s74, v211, v208
	v_add3_u32 v254, s74, v212, v208
	ds_read_b128 v[234:237], v215 offset:49152
	ds_read_b128 v[238:241], v215 offset:57344
	ds_read_b128 v[242:245], v216 offset:49152
	ds_read_b128 v[246:249], v216 offset:57344
	ds_read_b128 v[250:253], v233 offset:49152
.LBB0_309:
	s_mov_b32 s77, s74
	s_add_u32 s4, s70, 0xffffc000
	s_mov_b32 s74, s72
	s_addc_u32 s5, s71, -1
	s_add_i32 s72, s72, s42
	s_setprio 1
	s_waitcnt lgkmcnt(4)
	v_mfma_f32_32x32x16_bf16 v[112:127], v[234:237], v[188:191], 0
	ds_read_b128 v[234:237], v233 offset:57344
	v_add_f32_e32 v1, 0, v230
	v_add_f32_e32 v1, v232, v1
	v_add_f32_e32 v1, v228, v1
	v_add_f32_e32 v1, v231, v1
	v_add_f32_e32 v1, v226, v1
	s_waitcnt lgkmcnt(4)
	v_mfma_f32_32x32x16_bf16 v[96:111], v[238:241], v[188:191], 0
	ds_read_b128 v[238:241], v254 offset:49152
	v_add_f32_e32 v1, v229, v1
	v_add_f32_e32 v1, v225, v1
	v_add_f32_e32 v1, v227, v1
	v_add_f32_e32 v1, v222, v1
	v_add_f32_e32 v1, v224, v1
	s_waitcnt lgkmcnt(4)
	v_mfma_f32_32x32x16_bf16 v[112:127], v[242:245], v[184:187], v[112:127]
	ds_read_b128 v[242:245], v254 offset:57344
	s_mov_b32 s73, m0
	s_mov_b32 m0, s72
	s_nop 0
	global_load_lds_dwordx4 v197, s[4:5]
	s_mov_b32 m0, s73
	v_add_f32_e32 v1, v220, v1
	v_add_f32_e32 v1, v223, v1
	v_exp_f32_e32 v2, v128
	v_add_f32_e32 v1, v218, v1
	s_waitcnt lgkmcnt(4)
	v_mfma_f32_32x32x16_bf16 v[96:111], v[246:249], v[184:187], v[96:111]
	ds_read_b128 v[246:249], v215 offset:49280
	v_exp_f32_e32 v12, v129
	v_add_f32_e32 v1, v221, v1
	v_exp_f32_e32 v13, v130
	v_add_f32_e32 v1, v217, v1
	s_waitcnt lgkmcnt(4)
	v_mfma_f32_32x32x16_bf16 v[112:127], v[250:253], v[180:183], v[112:127]
	ds_read_b128 v[250:253], v215 offset:57472
	v_exp_f32_e32 v14, v131
	v_add_f32_e32 v1, v219, v1
	v_exp_f32_e32 v15, v132
	s_waitcnt lgkmcnt(4)
	v_mfma_f32_32x32x16_bf16 v[96:111], v[234:237], v[180:183], v[96:111]
	ds_read_b128 v[234:237], v216 offset:49280
	s_addk_i32 s72, 0x400
	s_mov_b32 s73, m0
	s_mov_b32 m0, s72
	s_nop 0
	global_load_lds_dwordx4 v198, s[4:5]
	s_mov_b32 m0, s73
	v_add_f32_e32 v1, v2, v1
	v_exp_f32_e32 v18, v133
	v_add_f32_e32 v1, v12, v1
	s_waitcnt lgkmcnt(4)
	v_mfma_f32_32x32x16_bf16 v[112:127], v[238:241], v[176:179], v[112:127]
	ds_read_b128 v[238:241], v216 offset:57472
	v_exp_f32_e32 v19, v134
	v_add_f32_e32 v1, v13, v1
	v_exp_f32_e32 v20, v135
	v_add_f32_e32 v1, v14, v1
	s_waitcnt lgkmcnt(4)
	v_mfma_f32_32x32x16_bf16 v[96:111], v[242:245], v[176:179], v[96:111]
	ds_read_b128 v[242:245], v233 offset:49280
	v_exp_f32_e32 v21, v136
	v_add_f32_e32 v1, v15, v1
	v_exp_f32_e32 v22, v137
	s_waitcnt lgkmcnt(4)
	v_mfma_f32_32x32x16_bf16 v[112:127], v[246:249], v[172:175], v[112:127]
	ds_read_b128 v[246:249], v233 offset:57472
	s_add_i32 s4, s69, s97
	s_mov_b32 s5, m0
	s_mov_b32 m0, s4
	s_nop 0
	global_load_lds_dwordx4 v199, s[56:57]
	s_mov_b32 m0, s5
	v_add_f32_e32 v1, v18, v1
	v_exp_f32_e32 v23, v138
	v_add_f32_e32 v1, v19, v1
	v_exp_f32_e32 v24, v139
	s_waitcnt lgkmcnt(4)
	v_mfma_f32_32x32x16_bf16 v[96:111], v[250:253], v[172:175], v[96:111]
	ds_read_b128 v[250:253], v254 offset:49280
	v_add_f32_e32 v1, v20, v1
	v_exp_f32_e32 v25, v140
	v_add_f32_e32 v1, v21, v1
	s_waitcnt lgkmcnt(4)
	v_mfma_f32_32x32x16_bf16 v[112:127], v[234:237], v[168:171], v[112:127]
	ds_read_b128 v[234:237], v254 offset:57472
	v_exp_f32_e32 v26, v141
	v_add_f32_e32 v1, v22, v1
	v_exp_f32_e32 v27, v142
	v_add_f32_e32 v1, v23, v1
	s_waitcnt lgkmcnt(4)
	v_mfma_f32_32x32x16_bf16 v[96:111], v[238:241], v[168:171], v[96:111]
	s_addk_i32 s4, 0x400
	s_mov_b32 s5, m0
	s_mov_b32 m0, s4
	s_nop 0
	global_load_lds_dwordx4 v200, s[56:57]
	s_mov_b32 m0, s5
	v_exp_f32_e32 v28, v143
	v_add_f32_e32 v1, v24, v1
	v_add_f32_e32 v1, v25, v1
	v_add_f32_e32 v1, v26, v1
	s_waitcnt lgkmcnt(3)
	v_mfma_f32_32x32x16_bf16 v[112:127], v[242:245], v[164:167], v[112:127]
	v_add_f32_e32 v1, v27, v1
	v_add_f32_e32 v1, v28, v1
	v_mov_b32_e32 v3, v1
	v_cvt_pk_bf16_f32 v4, v230, v232
	v_cvt_pk_bf16_f32 v5, v228, v231
	s_waitcnt lgkmcnt(2)
	v_mfma_f32_32x32x16_bf16 v[96:111], v[246:249], v[164:167], v[96:111]
	v_cvt_pk_bf16_f32 v6, v226, v229
	s_nop 1
	v_permlane32_swap_b32_e32 v1, v3
	v_cvt_pk_bf16_f32 v7, v225, v227
	v_cvt_pk_bf16_f32 v8, v222, v224
	v_cvt_pk_bf16_f32 v9, v220, v223
	s_waitcnt lgkmcnt(1)
	v_mfma_f32_32x32x16_bf16 v[112:127], v[250:253], v[160:163], v[112:127]
	v_cvt_pk_bf16_f32 v10, v218, v221
	v_cvt_pk_bf16_f32 v11, v217, v219
	v_cvt_pk_bf16_f32 v12, v2, v12
	v_cvt_pk_bf16_f32 v13, v13, v14
	v_cvt_pk_bf16_f32 v14, v15, v18
	s_waitcnt lgkmcnt(0)
	v_mfma_f32_32x32x16_bf16 v[96:111], v[234:237], v[160:163], v[96:111]
	v_cvt_pk_bf16_f32 v15, v19, v20
	v_cvt_pk_bf16_f32 v18, v21, v22
	v_cvt_pk_bf16_f32 v19, v23, v24
	v_cvt_pk_bf16_f32 v20, v25, v26
	v_cvt_pk_bf16_f32 v21, v27, v28
	s_setprio 0
	v_add_u32_e32 v2, s74, v206
	ds_read_b64_tr_b16 v[22:23], v2 offset:0
	ds_read_b64_tr_b16 v[24:25], v2 offset:0x800
	ds_read_b64_tr_b16 v[26:27], v2 offset:0x1000
	ds_read_b64_tr_b16 v[28:29], v2 offset:0x1800
	ds_read_b64_tr_b16 v[128:129], v2 offset:0x2000
	ds_read_b64_tr_b16 v[130:131], v2 offset:0x2800
	ds_read_b64_tr_b16 v[132:133], v2 offset:0x3000
	ds_read_b64_tr_b16 v[134:135], v2 offset:0x3800
	s_waitcnt lgkmcnt(6)
	s_nop 0
	v_mfma_f32_32x32x16_bf16 v[32:47], v[4:7], v[22:25], v[32:47]
	ds_read_b64_tr_b16 v[22:23], v2 offset:0x200
	ds_read_b64_tr_b16 v[24:25], v2 offset:0xa00
	s_waitcnt lgkmcnt(6)
	v_mfma_f32_32x32x16_bf16 v[32:47], v[8:11], v[26:29], v[32:47]
	ds_read_b64_tr_b16 v[26:27], v2 offset:0x1200
	ds_read_b64_tr_b16 v[28:29], v2 offset:0x1a00
	s_waitcnt lgkmcnt(6)
	v_mfma_f32_32x32x16_bf16 v[32:47], v[12:15], v[128:131], v[32:47]
	ds_read_b64_tr_b16 v[128:129], v2 offset:0x2200
	ds_read_b64_tr_b16 v[130:131], v2 offset:0x2a00
	s_waitcnt lgkmcnt(6)
	v_mfma_f32_32x32x16_bf16 v[32:47], v[18:21], v[132:135], v[32:47]
	ds_read_b64_tr_b16 v[132:133], v2 offset:0x3200
	ds_read_b64_tr_b16 v[134:135], v2 offset:0x3a00
	s_waitcnt lgkmcnt(6)
	v_mfma_f32_32x32x16_bf16 v[48:63], v[4:7], v[22:25], v[48:63]
	ds_read_b64_tr_b16 v[22:23], v2 offset:0x400
	ds_read_b64_tr_b16 v[24:25], v2 offset:0xc00
	s_waitcnt lgkmcnt(6)
	v_mfma_f32_32x32x16_bf16 v[48:63], v[8:11], v[26:29], v[48:63]
	ds_read_b64_tr_b16 v[26:27], v2 offset:0x1400
	ds_read_b64_tr_b16 v[28:29], v2 offset:0x1c00
	s_waitcnt lgkmcnt(6)
	v_mfma_f32_32x32x16_bf16 v[48:63], v[12:15], v[128:131], v[48:63]
	ds_read_b64_tr_b16 v[128:129], v2 offset:0x2400
	ds_read_b64_tr_b16 v[130:131], v2 offset:0x2c00
	s_waitcnt lgkmcnt(6)
	v_mfma_f32_32x32x16_bf16 v[48:63], v[18:21], v[132:135], v[48:63]
	ds_read_b64_tr_b16 v[132:133], v2 offset:0x3400
	ds_read_b64_tr_b16 v[134:135], v2 offset:0x3c00
	s_waitcnt lgkmcnt(6)
	v_mfma_f32_32x32x16_bf16 v[64:79], v[4:7], v[22:25], v[64:79]
	ds_read_b64_tr_b16 v[22:23], v2 offset:0x600
	ds_read_b64_tr_b16 v[24:25], v2 offset:0xe00
	v_add3_u32 v215, s69, v209, v208
	s_waitcnt lgkmcnt(6)
	v_mfma_f32_32x32x16_bf16 v[64:79], v[8:11], v[26:29], v[64:79]
	ds_read_b64_tr_b16 v[26:27], v2 offset:0x1600
	ds_read_b64_tr_b16 v[28:29], v2 offset:0x1e00
	v_add3_u32 v216, s69, v210, v208
	s_waitcnt lgkmcnt(6)
	v_mfma_f32_32x32x16_bf16 v[64:79], v[12:15], v[128:131], v[64:79]
	ds_read_b64_tr_b16 v[128:129], v2 offset:0x2600
	ds_read_b64_tr_b16 v[130:131], v2 offset:0x2e00
	v_add3_u32 v233, s69, v211, v208
	s_waitcnt lgkmcnt(6)
	v_mfma_f32_32x32x16_bf16 v[64:79], v[18:21], v[132:135], v[64:79]
	ds_read_b64_tr_b16 v[132:133], v2 offset:0x3600
	ds_read_b64_tr_b16 v[134:135], v2 offset:0x3e00
	v_add3_u32 v254, s69, v212, v208
	s_waitcnt lgkmcnt(6)
	v_mfma_f32_32x32x16_bf16 v[80:95], v[4:7], v[22:25], v[80:95]
	v_max_f32_e32 v2, v113, v112
	v_max3_f32 v2, v2, v114, v115
	v_max3_f32 v2, v2, v116, v117
	v_max3_f32 v2, v2, v118, v119
	v_max3_f32 v2, v2, v120, v121
	v_max3_f32 v2, v2, v122, v123
	v_max3_f32 v2, v2, v124, v125
	v_max3_f32 v2, v2, v126, v127
	s_waitcnt lgkmcnt(4)
	v_mfma_f32_32x32x16_bf16 v[80:95], v[8:11], v[26:29], v[80:95]
	v_max3_f32 v2, v2, v96, v97
	v_max3_f32 v2, v2, v98, v99
	v_max3_f32 v2, v2, v100, v101
	v_max3_f32 v2, v2, v102, v103
	v_max3_f32 v2, v2, v104, v105
	v_max3_f32 v2, v2, v106, v107
	v_max3_f32 v2, v2, v108, v109
	v_max3_f32 v2, v2, v110, v111
	s_waitcnt lgkmcnt(2)
	v_mfma_f32_32x32x16_bf16 v[80:95], v[12:15], v[128:131], v[80:95]
	v_mov_b32_e32 v4, v2
	s_nop 1
	v_permlane32_swap_b32_e32 v2, v4
	v_max_f32_e32 v2, v4, v2
	v_sub_f32_e32 v4, v2, v214
	v_cmp_ge_f32_e32 vcc, 0x42b504f3, v4
	v_max_f32_e32 v2, v214, v2
	s_waitcnt lgkmcnt(0)
	v_mfma_f32_32x32x16_bf16 v[80:95], v[18:21], v[132:135], v[80:95]
	s_cmp_eq_u64 vcc, exec
	s_cbranch_scc0 .Lattn0_slowA
	v_mov_b32_e32 v4, 1.0
	v_mov_b32_e32 v2, v214
.Lattn0_backA:
	s_waitcnt vmcnt(4) lgkmcnt(0)
	s_barrier
	ds_read_b128 v[234:237], v215 offset:49152
	ds_read_b128 v[238:241], v215 offset:57344
	ds_read_b128 v[242:245], v216 offset:49152
	ds_read_b128 v[246:249], v216 offset:57344
	ds_read_b128 v[250:253], v233 offset:49152
	v_mul_f32_e32 v5, 0xbe0293ee, v2
	v_fmamk_f32 v6, v112, 0x3e0293ee, v5
	v_fmamk_f32 v7, v113, 0x3e0293ee, v5
	v_fmamk_f32 v8, v114, 0x3e0293ee, v5
	v_fmamk_f32 v9, v115, 0x3e0293ee, v5
	v_fmamk_f32 v10, v116, 0x3e0293ee, v5
	v_fmamk_f32 v11, v117, 0x3e0293ee, v5
	v_fmamk_f32 v12, v118, 0x3e0293ee, v5
	v_fmamk_f32 v13, v119, 0x3e0293ee, v5
	v_fmamk_f32 v14, v120, 0x3e0293ee, v5
	v_fmamk_f32 v15, v121, 0x3e0293ee, v5
	v_fmamk_f32 v18, v122, 0x3e0293ee, v5
	v_fmamk_f32 v19, v123, 0x3e0293ee, v5
	v_fmamk_f32 v20, v124, 0x3e0293ee, v5
	v_fmamk_f32 v21, v125, 0x3e0293ee, v5
	v_fmamk_f32 v22, v126, 0x3e0293ee, v5
	v_fmamk_f32 v23, v127, 0x3e0293ee, v5
	v_fmamk_f32 v24, v96, 0x3e0293ee, v5
	v_fmamk_f32 v25, v97, 0x3e0293ee, v5
	v_fmamk_f32 v26, v98, 0x3e0293ee, v5
	v_fmamk_f32 v27, v99, 0x3e0293ee, v5
	v_fmamk_f32 v28, v100, 0x3e0293ee, v5
	v_fmamk_f32 v29, v101, 0x3e0293ee, v5
	v_fmamk_f32 v30, v102, 0x3e0293ee, v5
	v_fmamk_f32 v31, v103, 0x3e0293ee, v5
	v_fmamk_f32 v128, v104, 0x3e0293ee, v5
	v_fmamk_f32 v129, v105, 0x3e0293ee, v5
	v_fmamk_f32 v130, v106, 0x3e0293ee, v5
	v_fmamk_f32 v131, v107, 0x3e0293ee, v5
	v_fmamk_f32 v132, v108, 0x3e0293ee, v5
	v_fmamk_f32 v133, v109, 0x3e0293ee, v5
	v_fmamk_f32 v134, v110, 0x3e0293ee, v5
	v_fmac_f32_e32 v5, 0x3e0293ee, v111
	s_setprio 1
	s_waitcnt lgkmcnt(4)
	v_mfma_f32_32x32x16_bf16 v[112:127], v[234:237], v[188:191], 0
	ds_read_b128 v[234:237], v233 offset:57344
	v_exp_f32_e32 v135, v6
	v_exp_f32_e32 v136, v7
	v_exp_f32_e32 v137, v8
	v_exp_f32_e32 v138, v9
	s_waitcnt lgkmcnt(4)
	v_mfma_f32_32x32x16_bf16 v[96:111], v[238:241], v[188:191], 0
	ds_read_b128 v[238:241], v254 offset:49152
	v_exp_f32_e32 v10, v10
	v_exp_f32_e32 v11, v11
	v_exp_f32_e32 v12, v12
	s_waitcnt lgkmcnt(4)
	v_mfma_f32_32x32x16_bf16 v[112:127], v[242:245], v[184:187], v[112:127]
	ds_read_b128 v[242:245], v254 offset:57344
	s_add_i32 s4, s77, s42
	s_mov_b32 s5, m0
	s_mov_b32 m0, s4
	s_nop 0
	global_load_lds_dwordx4 v197, s[70:71]
	s_mov_b32 m0, s5
	v_exp_f32_e32 v13, v13
	v_exp_f32_e32 v14, v14
	v_exp_f32_e32 v15, v15
	v_exp_f32_e32 v18, v18
	s_waitcnt lgkmcnt(4)
	v_mfma_f32_32x32x16_bf16 v[96:111], v[246:249], v[184:187], v[96:111]
	ds_read_b128 v[246:249], v215 offset:49280
	v_exp_f32_e32 v19, v19
	v_exp_f32_e32 v20, v20
	v_exp_f32_e32 v21, v21
	s_waitcnt lgkmcnt(4)
	v_mfma_f32_32x32x16_bf16 v[112:127], v[250:253], v[180:183], v[112:127]
	ds_read_b128 v[250:253], v215 offset:57472
	v_exp_f32_e32 v22, v22
	v_exp_f32_e32 v23, v23
	v_exp_f32_e32 v7, v24
	v_exp_f32_e32 v24, v25
	s_waitcnt lgkmcnt(4)
	v_mfma_f32_32x32x16_bf16 v[96:111], v[234:237], v[180:183], v[96:111]
	ds_read_b128 v[234:237], v216 offset:49280
	s_addk_i32 s4, 0x400
	s_mov_b32 s5, m0
	s_mov_b32 m0, s4
	s_nop 0
	global_load_lds_dwordx4 v198, s[70:71]
	s_mov_b32 m0, s5
	v_exp_f32_e32 v25, v26
	v_exp_f32_e32 v26, v27
	v_exp_f32_e32 v27, v28
	s_waitcnt lgkmcnt(4)
	v_mfma_f32_32x32x16_bf16 v[112:127], v[238:241], v[176:179], v[112:127]
	ds_read_b128 v[238:241], v216 offset:57472
	v_exp_f32_e32 v28, v29
	v_exp_f32_e32 v29, v30
	v_exp_f32_e32 v30, v31
	v_exp_f32_e32 v31, v128
	s_waitcnt lgkmcnt(4)
	v_mfma_f32_32x32x16_bf16 v[96:111], v[242:245], v[176:179], v[96:111]
	ds_read_b128 v[242:245], v233 offset:49280
	v_exp_f32_e32 v128, v129
	v_exp_f32_e32 v129, v130
	v_exp_f32_e32 v130, v131
	v_exp_f32_e32 v131, v132
	s_waitcnt lgkmcnt(4)
	v_mfma_f32_32x32x16_bf16 v[112:127], v[246:249], v[172:175], v[112:127]
	ds_read_b128 v[246:249], v233 offset:57472
	s_add_u32 s4, s56, 0x4000
	s_addc_u32 s5, s57, 0
	s_add_i32 s72, s74, s97
	s_mov_b32 s73, m0
	s_mov_b32 m0, s72
	s_nop 0
	global_load_lds_dwordx4 v199, s[4:5]
	s_mov_b32 m0, s73
	v_exp_f32_e32 v132, v133
	v_exp_f32_e32 v133, v134
	v_exp_f32_e32 v134, v5
	s_waitcnt lgkmcnt(4)
	v_mfma_f32_32x32x16_bf16 v[96:111], v[250:253], v[172:175], v[96:111]
	ds_read_b128 v[250:253], v254 offset:49280
	v_add_f32_e32 v5, 0, v135
	v_add_f32_e32 v5, v136, v5
	v_add_f32_e32 v5, v137, v5
	v_add_f32_e32 v5, v138, v5
	v_add_f32_e32 v5, v10, v5
	v_add_f32_e32 v5, v11, v5
	v_add_f32_e32 v5, v12, v5
	v_add_f32_e32 v5, v13, v5
	s_waitcnt lgkmcnt(4)
	v_mfma_f32_32x32x16_bf16 v[112:127], v[234:237], v[168:171], v[112:127]
	ds_read_b128 v[234:237], v254 offset:57472
	v_add_f32_e32 v5, v14, v5
	v_add_f32_e32 v5, v15, v5
	v_add_f32_e32 v5, v18, v5
	v_add_f32_e32 v5, v19, v5
	v_add_f32_e32 v5, v20, v5
	v_add_f32_e32 v5, v21, v5
	v_add_f32_e32 v5, v22, v5
	s_waitcnt lgkmcnt(4)
	v_mfma_f32_32x32x16_bf16 v[96:111], v[238:241], v[168:171], v[96:111]
	s_addk_i32 s72, 0x400
	s_mov_b32 s73, m0
	s_mov_b32 m0, s72
	s_nop 0
	global_load_lds_dwordx4 v200, s[4:5]
	s_mov_b32 m0, s73
	v_add_f32_e32 v5, v23, v5
	v_add_f32_e32 v5, v7, v5
	v_add_f32_e32 v5, v24, v5
	v_add_f32_e32 v5, v25, v5
	v_add_f32_e32 v5, v26, v5
	v_add_f32_e32 v5, v27, v5
	v_add_f32_e32 v5, v28, v5
	s_waitcnt lgkmcnt(3)
	v_mfma_f32_32x32x16_bf16 v[112:127], v[242:245], v[164:167], v[112:127]
	v_add_f32_e32 v5, v29, v5
	v_add_f32_e32 v5, v30, v5
	v_add_f32_e32 v5, v31, v5
	v_add_f32_e32 v5, v128, v5
	v_add_f32_e32 v5, v129, v5
	v_add_f32_e32 v5, v130, v5
	v_add_f32_e32 v5, v131, v5
	s_waitcnt lgkmcnt(2)
	v_mfma_f32_32x32x16_bf16 v[96:111], v[246:249], v[164:167], v[96:111]
	v_add_f32_e32 v5, v132, v5
	v_add_f32_e32 v5, v133, v5
	v_add_f32_e32 v5, v134, v5
	v_mov_b32_e32 v6, v5
	v_cvt_pk_bf16_f32 v8, v135, v136
	v_cvt_pk_bf16_f32 v9, v137, v138
	v_cvt_pk_bf16_f32 v10, v10, v11
	s_waitcnt lgkmcnt(1)
	v_mfma_f32_32x32x16_bf16 v[112:127], v[250:253], v[160:163], v[112:127]
	s_nop 1
	v_permlane32_swap_b32_e32 v5, v6
	v_cvt_pk_bf16_f32 v11, v12, v13
	v_cvt_pk_bf16_f32 v12, v14, v15
	v_cvt_pk_bf16_f32 v13, v18, v19
	v_cvt_pk_bf16_f32 v14, v20, v21
	v_cvt_pk_bf16_f32 v15, v22, v23
	v_cvt_pk_bf16_f32 v18, v7, v24
	s_waitcnt lgkmcnt(0)
	v_mfma_f32_32x32x16_bf16 v[96:111], v[234:237], v[160:163], v[96:111]
	v_cvt_pk_bf16_f32 v19, v25, v26
	v_cvt_pk_bf16_f32 v20, v27, v28
	v_cvt_pk_bf16_f32 v21, v29, v30
	v_cvt_pk_bf16_f32 v22, v31, v128
	v_cvt_pk_bf16_f32 v23, v129, v130
	v_cvt_pk_bf16_f32 v24, v131, v132
	v_cvt_pk_bf16_f32 v25, v133, v134
	s_setprio 0
	v_add_u32_e32 v7, s77, v206
	ds_read_b64_tr_b16 v[26:27], v7 offset:0
	ds_read_b64_tr_b16 v[28:29], v7 offset:0x800
	ds_read_b64_tr_b16 v[128:129], v7 offset:0x1000
	ds_read_b64_tr_b16 v[130:131], v7 offset:0x1800
	ds_read_b64_tr_b16 v[132:133], v7 offset:0x2000
	ds_read_b64_tr_b16 v[134:135], v7 offset:0x2800
	ds_read_b64_tr_b16 v[136:137], v7 offset:0x3000
	ds_read_b64_tr_b16 v[138:139], v7 offset:0x3800
	s_waitcnt lgkmcnt(6)
	s_nop 0
	v_mfma_f32_32x32x16_bf16 v[32:47], v[8:11], v[26:29], v[32:47]
	ds_read_b64_tr_b16 v[26:27], v7 offset:0x200
	ds_read_b64_tr_b16 v[28:29], v7 offset:0xa00
	s_waitcnt lgkmcnt(6)
	v_mfma_f32_32x32x16_bf16 v[32:47], v[12:15], v[128:131], v[32:47]
	ds_read_b64_tr_b16 v[128:129], v7 offset:0x1200
	ds_read_b64_tr_b16 v[130:131], v7 offset:0x1a00
	v_mul_f32_e32 v140, 0xbe0293ee, v2
	v_fmamk_f32 v230, v112, 0x3e0293ee, v140
	v_fmamk_f32 v232, v113, 0x3e0293ee, v140
	s_waitcnt lgkmcnt(6)
	v_mfma_f32_32x32x16_bf16 v[32:47], v[18:21], v[132:135], v[32:47]
	ds_read_b64_tr_b16 v[132:133], v7 offset:0x2200
	ds_read_b64_tr_b16 v[134:135], v7 offset:0x2a00
	v_exp_f32_e32 v230, v230
	v_exp_f32_e32 v232, v232
	v_fmamk_f32 v228, v114, 0x3e0293ee, v140
	v_fmamk_f32 v231, v115, 0x3e0293ee, v140
	s_waitcnt lgkmcnt(6)
	v_mfma_f32_32x32x16_bf16 v[32:47], v[22:25], v[136:139], v[32:47]
	ds_read_b64_tr_b16 v[136:137], v7 offset:0x3200
	ds_read_b64_tr_b16 v[138:139], v7 offset:0x3a00
	v_exp_f32_e32 v228, v228
	v_exp_f32_e32 v231, v231
	v_fmamk_f32 v226, v116, 0x3e0293ee, v140
	v_fmamk_f32 v229, v117, 0x3e0293ee, v140
	s_waitcnt lgkmcnt(6)
	v_mfma_f32_32x32x16_bf16 v[48:63], v[8:11], v[26:29], v[48:63]
	ds_read_b64_tr_b16 v[26:27], v7 offset:0x400
	ds_read_b64_tr_b16 v[28:29], v7 offset:0xc00
	v_exp_f32_e32 v226, v226
	v_exp_f32_e32 v229, v229
	v_fmamk_f32 v225, v118, 0x3e0293ee, v140
	v_fmamk_f32 v227, v119, 0x3e0293ee, v140
	s_waitcnt lgkmcnt(6)
	v_mfma_f32_32x32x16_bf16 v[48:63], v[12:15], v[128:131], v[48:63]
	ds_read_b64_tr_b16 v[128:129], v7 offset:0x1400
	ds_read_b64_tr_b16 v[130:131], v7 offset:0x1c00
	v_exp_f32_e32 v225, v225
	v_exp_f32_e32 v227, v227
	v_fmamk_f32 v222, v120, 0x3e0293ee, v140
	v_fmamk_f32 v224, v121, 0x3e0293ee, v140
	s_waitcnt lgkmcnt(6)
	v_mfma_f32_32x32x16_bf16 v[48:63], v[18:21], v[132:135], v[48:63]
	ds_read_b64_tr_b16 v[132:133], v7 offset:0x2400
	ds_read_b64_tr_b16 v[134:135], v7 offset:0x2c00
	v_exp_f32_e32 v222, v222
	v_exp_f32_e32 v224, v224
	v_fmamk_f32 v220, v122, 0x3e0293ee, v140
	v_fmamk_f32 v223, v123, 0x3e0293ee, v140
	s_waitcnt lgkmcnt(6)
	v_mfma_f32_32x32x16_bf16 v[48:63], v[22:25], v[136:139], v[48:63]
	ds_read_b64_tr_b16 v[136:137], v7 offset:0x3400
	ds_read_b64_tr_b16 v[138:139], v7 offset:0x3c00
	v_exp_f32_e32 v220, v220
	v_exp_f32_e32 v223, v223
	v_fmamk_f32 v218, v124, 0x3e0293ee, v140
	v_fmamk_f32 v221, v125, 0x3e0293ee, v140
	s_waitcnt lgkmcnt(6)
	v_mfma_f32_32x32x16_bf16 v[64:79], v[8:11], v[26:29], v[64:79]
	ds_read_b64_tr_b16 v[26:27], v7 offset:0x600
	ds_read_b64_tr_b16 v[28:29], v7 offset:0xe00
	v_exp_f32_e32 v218, v218
	v_exp_f32_e32 v221, v221
	v_fmamk_f32 v217, v126, 0x3e0293ee, v140
	v_fmamk_f32 v219, v127, 0x3e0293ee, v140
	s_waitcnt lgkmcnt(6)
	v_mfma_f32_32x32x16_bf16 v[64:79], v[12:15], v[128:131], v[64:79]
	ds_read_b64_tr_b16 v[128:129], v7 offset:0x1600
	ds_read_b64_tr_b16 v[130:131], v7 offset:0x1e00
	v_exp_f32_e32 v217, v217
	v_exp_f32_e32 v219, v219
	s_waitcnt lgkmcnt(6)
	v_mfma_f32_32x32x16_bf16 v[64:79], v[18:21], v[132:135], v[64:79]
	ds_read_b64_tr_b16 v[132:133], v7 offset:0x2600
	ds_read_b64_tr_b16 v[134:135], v7 offset:0x2e00
	v_add3_u32 v215, s74, v209, v208
	v_add3_u32 v216, s74, v210, v208
	s_waitcnt lgkmcnt(6)
	v_mfma_f32_32x32x16_bf16 v[64:79], v[22:25], v[136:139], v[64:79]
	ds_read_b64_tr_b16 v[136:137], v7 offset:0x3600
	ds_read_b64_tr_b16 v[138:139], v7 offset:0x3e00
	v_add3_u32 v233, s74, v211, v208
	v_add3_u32 v254, s74, v212, v208
	s_waitcnt lgkmcnt(6)
	v_mfma_f32_32x32x16_bf16 v[80:95], v[8:11], v[26:29], v[80:95]
	v_max_f32_e32 v7, v113, v112
	v_max3_f32 v7, v7, v114, v115
	v_max3_f32 v7, v7, v116, v117
	v_max3_f32 v7, v7, v118, v119
	v_max3_f32 v7, v7, v120, v121
	v_max3_f32 v7, v7, v122, v123
	v_max3_f32 v7, v7, v124, v125
	v_max3_f32 v7, v7, v126, v127
	s_waitcnt lgkmcnt(4)
	v_mfma_f32_32x32x16_bf16 v[80:95], v[12:15], v[128:131], v[80:95]
	v_max3_f32 v7, v7, v96, v97
	v_max3_f32 v7, v7, v98, v99
	v_max3_f32 v7, v7, v100, v101
	v_max3_f32 v7, v7, v102, v103
	v_max3_f32 v7, v7, v104, v105
	v_max3_f32 v7, v7, v106, v107
	v_max3_f32 v7, v7, v108, v109
	v_max3_f32 v7, v7, v110, v111
	s_waitcnt lgkmcnt(2)
	v_mfma_f32_32x32x16_bf16 v[80:95], v[18:21], v[132:135], v[80:95]
	v_mov_b32_e32 v8, v7
	s_nop 1
	v_permlane32_swap_b32_e32 v7, v8
	v_max_f32_e32 v7, v8, v7
	v_sub_f32_e32 v8, v7, v2
	v_cmp_ge_f32_e32 vcc, 0x42b504f3, v8
	v_max_f32_e32 v8, v2, v7
	s_waitcnt lgkmcnt(0)
	v_mfma_f32_32x32x16_bf16 v[80:95], v[22:25], v[136:139], v[80:95]
	s_cmp_eq_u64 vcc, exec
	s_cbranch_scc0 .Lattn0_slowB
	v_mov_b32_e32 v7, 1.0
	v_mov_b32_e32 v214, v2
.Lattn0_backB:
	v_mul_f32_e32 v2, 0xbe0293ee, v214
	v_add_f32_e32 v1, v1, v3
	s_add_u32 s56, s56, 0x8000
	s_addc_u32 s57, s57, 0
	s_add_i32 s4, s45, 2
	s_add_u32 s70, s70, 0x8000
	s_addc_u32 s71, s71, 0
	s_waitcnt vmcnt(4) lgkmcnt(0)
	s_barrier
	ds_read_b128 v[234:237], v215 offset:49152
	ds_read_b128 v[238:241], v215 offset:57344
	ds_read_b128 v[242:245], v216 offset:49152
	ds_read_b128 v[246:249], v216 offset:57344
	ds_read_b128 v[250:253], v233 offset:49152
	v_fmac_f32_e32 v1, v213, v205
	v_add_f32_e32 v205, v5, v6
	v_fmac_f32_e32 v205, v1, v4
	v_pk_fma_f32 v[142:143], v[110:111], s[12:13], v[2:3] op_sel_hi:[1,0,0]
	v_pk_fma_f32 v[140:141], v[108:109], s[12:13], v[2:3] op_sel_hi:[1,0,0]
	v_pk_fma_f32 v[138:139], v[106:107], s[12:13], v[2:3] op_sel_hi:[1,0,0]
	v_pk_fma_f32 v[136:137], v[104:105], s[12:13], v[2:3] op_sel_hi:[1,0,0]
	v_pk_fma_f32 v[134:135], v[102:103], s[12:13], v[2:3] op_sel_hi:[1,0,0]
	v_pk_fma_f32 v[132:133], v[100:101], s[12:13], v[2:3] op_sel_hi:[1,0,0]
	v_pk_fma_f32 v[130:131], v[98:99], s[12:13], v[2:3] op_sel_hi:[1,0,0]
	v_pk_fma_f32 v[128:129], v[96:97], s[12:13], v[2:3] op_sel_hi:[1,0,0]
	s_cmp_ge_i32 s4, s21
	s_cbranch_scc1 .Lattn0_exitB
	s_mov_b32 s45, s4
	s_mov_b32 s72, s69
	s_mov_b32 s69, s77
	v_mov_b32_e32 v213, v7
	s_branch .LBB0_309
.Lattn0_exitB:
	s_waitcnt lgkmcnt(0)
	s_branch .LBB0_321

.Lattn0_recompB:
	v_mul_f32_e32 v140, 0xbe0293ee, v214
	v_fmamk_f32 v230, v112, 0x3e0293ee, v140
	v_fmamk_f32 v232, v113, 0x3e0293ee, v140
	v_fmamk_f32 v228, v114, 0x3e0293ee, v140
	v_fmamk_f32 v231, v115, 0x3e0293ee, v140
	v_fmamk_f32 v226, v116, 0x3e0293ee, v140
	v_fmamk_f32 v229, v117, 0x3e0293ee, v140
	v_fmamk_f32 v225, v118, 0x3e0293ee, v140
	v_fmamk_f32 v227, v119, 0x3e0293ee, v140
	v_fmamk_f32 v222, v120, 0x3e0293ee, v140
	v_fmamk_f32 v224, v121, 0x3e0293ee, v140
	v_fmamk_f32 v220, v122, 0x3e0293ee, v140
	v_fmamk_f32 v223, v123, 0x3e0293ee, v140
	v_fmamk_f32 v218, v124, 0x3e0293ee, v140
	v_fmamk_f32 v221, v125, 0x3e0293ee, v140
	v_fmamk_f32 v217, v126, 0x3e0293ee, v140
	v_fmamk_f32 v219, v127, 0x3e0293ee, v140
	v_exp_f32_e32 v230, v230
	v_exp_f32_e32 v232, v232
	v_exp_f32_e32 v228, v228
	v_exp_f32_e32 v231, v231
	v_exp_f32_e32 v226, v226
	v_exp_f32_e32 v229, v229
	v_exp_f32_e32 v225, v225
	v_exp_f32_e32 v227, v227
	v_exp_f32_e32 v222, v222
	v_exp_f32_e32 v224, v224
	v_exp_f32_e32 v220, v220
	v_exp_f32_e32 v223, v223
	v_exp_f32_e32 v218, v218
	v_exp_f32_e32 v221, v221
	v_exp_f32_e32 v217, v217
	v_exp_f32_e32 v219, v219
	s_branch .Lattn0_backB
